# P40 + main attention unit prologue: first K/V tile LDS-DMA issued before the Q register->LDS wait ladder (latencies overlap)
# baseline (speedup 1.0000x reference)
.LBB0_692:
	s_and_b64 vcc, exec, s[4:5]
	s_cbranch_vccz .LBB0_783
	s_and_b32 s0, s22, 0x7fffffc0
	s_cmpk_lg_i32 s0, 0x1c0
	s_mov_b64 s[4:5], -1
	s_cbranch_scc0 .LBB0_745
	s_cmpk_lt_u32 s22, 0x200
	s_cbranch_scc1 .LBB0_744
	s_add_i32 s0, s22, 0xfffffe00
	v_mbcnt_lo_u32_b32 v0, -1, 0
	v_mbcnt_hi_u32_b32 v0, -1, v0
	s_lshr_b32 s4, s0, 5
	v_add_u32_e32 v36, s93, v0
	s_lshl_b32 s0, s22, 8
	s_lshl_b32 s12, s4, 11
	v_readfirstlane_b32 s2, v36
	s_and_b32 s0, s0, 0x700
	s_ashr_i32 s5, s2, 6
	s_or_b32 s0, s12, s0
	s_lshl_b32 s2, s5, 5
	v_readlane_b32 s8, v255, 11
	v_and_b32_e32 v0, 31, v36
	s_add_i32 s0, s2, s0
	v_readlane_b32 s9, v255, 12
	s_bfe_u32 s1, s22, 0x20003
	v_or_b32_e32 v4, s0, v0
	v_mov_b64_e32 v[2:3], s[8:9]
	v_bfe_u32 v37, v36, 5, 1
	v_mad_i64_i32 v[2:3], s[2:3], v4, s72, v[2:3]
	s_lshl_b32 s36, s1, 8
	v_lshl_add_u64 v[2:3], v[2:3], 0, s[36:37]
	v_lshlrev_b32_e32 v34, 4, v37
	v_mov_b32_e32 v35, v1
	v_lshl_add_u64 v[30:31], v[2:3], 0, v[34:35]
	global_load_dwordx4 v[2:5], v[30:31], off offset:2560
	global_load_dwordx4 v[6:9], v[30:31], off offset:2592
	global_load_dwordx4 v[10:13], v[30:31], off offset:2624
	global_load_dwordx4 v[14:17], v[30:31], off offset:2656
	global_load_dwordx4 v[18:21], v[30:31], off offset:2688
	global_load_dwordx4 v[22:25], v[30:31], off offset:2720
	global_load_dwordx4 v[26:29], v[30:31], off offset:2752
	s_nop 0
	global_load_dwordx4 v[30:33], v[30:31], off offset:2784
	v_lshlrev_b32_e32 v35, 4, v36
	v_and_b32_e32 v42, 0xf0, v35
	s_movk_i32 s6, 0x60
	v_bitop3_b32 v215, v34, v42, s6 bitop3:0x36
	s_movk_i32 s6, 0x80
	v_bitop3_b32 v216, v34, v42, s6 bitop3:0x36
	s_movk_i32 s6, 0xa0
	v_bitop3_b32 v217, v34, v42, s6 bitop3:0x36
	s_movk_i32 s6, 0xc0
	s_lshl_b32 s2, s5, 9
	s_lshl_b32 s3, s5, 13
	v_bitop3_b32 v218, v34, v42, s6 bitop3:0x36
	s_movk_i32 s6, 0xe0
	s_lshl_b32 s13, s4, 8
	v_bfe_u32 v38, v36, 4, 2
	v_bfe_u32 v39, v36, 2, 3
	v_bitop3_b32 v219, v34, v42, s6 bitop3:0x36
	s_lshl_b32 s6, s5, 3
	s_add_i32 s15, s3, 0
	s_add_i32 s14, s2, 0
	s_lshl_b32 s1, s1, 7
	s_add_i32 s13, s13, 0x8000
	v_lshlrev_b32_e32 v41, 3, v36
	v_or_b32_e32 v43, s6, v38
	v_or_b32_e32 v39, s6, v39
	s_add_i32 s15, s15, 0x11000
	s_add_i32 s14, s14, 0x10000
	s_movk_i32 s2, 0xb00
	v_and_b32_e32 v40, 32, v36
	v_lshlrev_b32_e32 v212, 8, v0
	v_bitop3_b32 v0, v37, v36, 15 bitop3:0x78
	v_and_b32_e32 v37, 24, v41
	v_bitop3_b32 v38, s6, v36, v38 bitop3:0x36
	v_mul_lo_u32 v39, v39, s2
	v_mul_lo_u32 v44, v43, s2
	v_bitop3_b32 v43, v43, v36, 4 bitop3:0x36
	s_add_u32 s36, s8, s36
	v_lshlrev_b32_e32 v38, 3, v38
	v_or3_b32 v37, v40, v37, v39
	s_movk_i32 s2, 0x78
	v_lshlrev_b32_e32 v39, 3, v43
	s_addc_u32 s38, s9, 0
	s_mul_i32 s4, s4, 0xb00000
	v_and_or_b32 v38, v38, s2, v44
	v_lshlrev_b32_e32 v196, 1, v37
	v_and_or_b32 v37, v39, s2, v44
	s_mul_hi_u32 s3, s12, 0x1600
	s_add_u32 s2, s36, s4
	v_add_u32_e32 v45, s15, v212
	s_addc_u32 s3, s38, s3
	s_lshl_b32 s6, s5, 11
	v_bitop3_b32 v213, v34, v42, 32 bitop3:0x36
	v_bitop3_b32 v214, v34, v42, 64 bitop3:0x36
	v_lshl_add_u32 v40, v0, 4, v45
	v_lshlrev_b32_e32 v0, 1, v38
	s_add_u32 s4, s2, 0x1200
	v_add_u32_e32 v43, v45, v213
	v_add_u32_e32 v46, v45, v214
	v_add_u32_e32 v47, v45, v215
	v_add_u32_e32 v48, v45, v216
	v_add_u32_e32 v49, v45, v217
	v_add_u32_e32 v50, v45, v218
	v_add_u32_e32 v45, v45, v219
	s_addc_u32 s5, s3, 0
	v_lshl_add_u64 v[52:53], s[2:3], 0, v[0:1]
	s_add_i32 s39, s6, 0
	v_lshl_add_u32 v198, v37, 1, v249
	v_lshl_add_u64 v[52:53], v[52:53], 0, s[26:27]
	s_add_i32 m0, s39, 0x8000
	v_mov_b32_e32 v199, v1
	global_load_lds_dwordx4 v[52:53], off
	s_mov_b32 m0, s39
	v_lshl_add_u64 v[52:53], s[2:3], 0, v[198:199]
	global_load_lds_dwordx4 v196, s[4:5]
	v_lshl_add_u64 v[52:53], v[52:53], 0, s[26:27]
	s_add_i32 m0, s39, 0x8400
	v_or_b32_e32 v200, 0x80, v196
	global_load_lds_dwordx4 v[52:53], off
	s_add_i32 m0, s39, 0x400
	s_nop 0
	global_load_lds_dwordx4 v200, s[4:5]
	s_waitcnt vmcnt(11)
	ds_write_b128 v40, v[2:5]
	s_waitcnt vmcnt(10)
	ds_write_b128 v43, v[6:9]
	s_waitcnt vmcnt(9)
	ds_write_b128 v46, v[10:13]
	s_waitcnt vmcnt(8)
	ds_write_b128 v47, v[14:17]
	s_waitcnt vmcnt(7)
	ds_write_b128 v48, v[18:21]
	s_waitcnt vmcnt(6)
	ds_write_b128 v49, v[22:25]
	s_waitcnt vmcnt(5)
	ds_write_b128 v50, v[26:29]
	s_waitcnt vmcnt(4)
	ds_write_b128 v45, v[30:33]
	v_or_b32_e32 v2, 32, v34
	v_lshlrev_b32_e32 v9, 1, v36
	v_and_b32_e32 v11, 0x118, v41
	v_or_b32_e32 v3, 64, v34
	v_or_b32_e32 v4, 0x60, v34
	v_or_b32_e32 v5, 0x80, v34
	v_or_b32_e32 v6, 0xa0, v34
	v_or_b32_e32 v7, 0xc0, v34
	v_or_b32_e32 v8, 0xe0, v34
	v_and_b32_e32 v10, 0xc0, v35
	s_waitcnt vmcnt(0)
	s_movk_i32 s2, 0xf0
	v_bitop3_b32 v222, v2, v212, v42 bitop3:0xde
	v_and_or_b32 v2, v9, 32, v11
	v_mov_b32_e32 v16, v1
	v_mov_b32_e32 v17, v1
	v_bitop3_b32 v220, v34, v35, s2 bitop3:0x78
	v_bitop3_b32 v221, v34, v212, v42 bitop3:0xde
	v_bitop3_b32 v223, v3, v212, v42 bitop3:0xde
	v_bitop3_b32 v224, v4, v212, v42 bitop3:0xde
	v_bitop3_b32 v225, v5, v212, v42 bitop3:0xde
	v_bitop3_b32 v226, v6, v212, v42 bitop3:0xde
	v_bitop3_b32 v227, v7, v212, v42 bitop3:0xde
	v_bitop3_b32 v228, v8, v212, v42 bitop3:0xde
	v_add3_u32 v229, v10, 0, v2
	v_mov_b32_e32 v2, v1
	v_mov_b32_e32 v3, v1
	v_mov_b32_e32 v4, v1
	v_mov_b32_e32 v5, v1
	v_mov_b32_e32 v6, v1
	v_mov_b32_e32 v7, v1
	v_mov_b32_e32 v8, v1
	v_mov_b32_e32 v9, v1
	v_mov_b32_e32 v10, v1
	v_mov_b32_e32 v11, v1
	v_mov_b32_e32 v12, v1
	v_mov_b32_e32 v13, v1
	v_mov_b32_e32 v14, v1
	v_mov_b32_e32 v15, v1
	v_mov_b64_e32 v[80:81], v[16:17]
	v_mov_b64_e32 v[48:49], v[16:17]
	v_mov_b64_e32 v[32:33], v[16:17]
	v_mov_b64_e32 v[128:129], v[16:17]
	v_mov_b64_e32 v[112:113], v[16:17]
	v_mov_b64_e32 v[96:97], v[16:17]
	v_mov_b64_e32 v[64:65], v[16:17]
	v_mov_b32_e32 v197, v1
	v_mov_b32_e32 v201, v1
	s_mov_b32 s40, 0
	v_mov_b32_e32 v202, v1
	v_mov_b32_e32 v203, v1
	v_mov_b32_e32 v231, 0
	s_mov_b64 s[4:5], 0
	s_mov_b64 s[6:7], -1
	v_mov_b64_e32 v[78:79], v[14:15]
	v_mov_b64_e32 v[76:77], v[12:13]
	v_mov_b64_e32 v[74:75], v[10:11]
	v_mov_b64_e32 v[72:73], v[8:9]
	v_mov_b64_e32 v[70:71], v[6:7]
	v_mov_b64_e32 v[68:69], v[4:5]
	v_mov_b64_e32 v[66:67], v[2:3]
	v_mov_b64_e32 v[46:47], v[14:15]
	v_mov_b64_e32 v[44:45], v[12:13]
	v_mov_b64_e32 v[42:43], v[10:11]
	v_mov_b64_e32 v[40:41], v[8:9]
	v_mov_b64_e32 v[38:39], v[6:7]
	v_mov_b64_e32 v[36:37], v[4:5]
	v_mov_b64_e32 v[34:35], v[2:3]
	v_mov_b64_e32 v[30:31], v[14:15]
	v_mov_b64_e32 v[28:29], v[12:13]
	v_mov_b64_e32 v[26:27], v[10:11]
	v_mov_b64_e32 v[24:25], v[8:9]
	v_mov_b64_e32 v[22:23], v[6:7]
	v_mov_b64_e32 v[20:21], v[4:5]
	v_mov_b64_e32 v[18:19], v[2:3]
	v_mov_b64_e32 v[126:127], v[14:15]
	v_mov_b64_e32 v[124:125], v[12:13]
	v_mov_b64_e32 v[122:123], v[10:11]
	v_mov_b64_e32 v[120:121], v[8:9]
	v_mov_b64_e32 v[118:119], v[6:7]
	v_mov_b64_e32 v[116:117], v[4:5]
	v_mov_b64_e32 v[114:115], v[2:3]
	v_mov_b64_e32 v[110:111], v[14:15]
	v_mov_b64_e32 v[108:109], v[12:13]
	v_mov_b64_e32 v[106:107], v[10:11]
	v_mov_b64_e32 v[104:105], v[8:9]
	v_mov_b64_e32 v[102:103], v[6:7]
	v_mov_b64_e32 v[100:101], v[4:5]
	v_mov_b64_e32 v[98:99], v[2:3]
	v_mov_b64_e32 v[94:95], v[14:15]
	v_mov_b64_e32 v[92:93], v[12:13]
	v_mov_b64_e32 v[90:91], v[10:11]
	v_mov_b64_e32 v[88:89], v[8:9]
	v_mov_b64_e32 v[86:87], v[6:7]
	v_mov_b64_e32 v[84:85], v[4:5]
	v_mov_b64_e32 v[82:83], v[2:3]
	v_mov_b64_e32 v[62:63], v[14:15]
	v_mov_b64_e32 v[60:61], v[12:13]
	v_mov_b64_e32 v[58:59], v[10:11]
	v_mov_b64_e32 v[56:57], v[8:9]
	v_mov_b64_e32 v[54:55], v[6:7]
	v_mov_b64_e32 v[52:53], v[4:5]
	v_mov_b64_e32 v[50:51], v[2:3]
	v_mov_b32_e32 v230, 0
	s_waitcnt vmcnt(0) lgkmcnt(0)
	s_barrier
	s_branch .LBB0_699
